# sample conv LayerNorm: both wave sums via DPP (no lgkmcnt coupling with the flat loads issued between the hops)
# baseline (speedup 1.0000x reference)
.LBB0_639:
	v_readlane_b32 s0, v239, 41
	v_readlane_b32 s2, v239, 42
	v_mov_b32_e32 v122, v0
	v_mov_b32_e32 v2, s0
	ds_read2_b64 v[2:5], v2 offset1:1
	s_mov_b32 s83, 0x15000
	s_mov_b32 s90, 0x17000
	s_mov_b32 s48, 0x18000
	s_mov_b32 s52, 0x19000
	s_waitcnt lgkmcnt(0)
	v_readfirstlane_b32 s0, v2
	v_mov_b32_e32 v2, s2
	v_readfirstlane_b32 s1, v3
	v_readfirstlane_b32 s35, v5
	v_readfirstlane_b32 s46, v4
	ds_read2_b64 v[2:5], v2 offset1:1
	v_readlane_b32 s2, v239, 43
	s_add_u32 s0, s0, s21
	s_addc_u32 s1, s1, s20
	s_ashr_i32 s18, s28, 31
	s_waitcnt lgkmcnt(0)
	v_readfirstlane_b32 s34, v2
	v_mov_b32_e32 v2, s2
	v_readfirstlane_b32 s19, v3
	ds_read_b64 v[2:3], v2
	s_movk_i32 s2, 0x5000
	v_lshlrev_b32_e32 v32, 1, v122
	v_ashrrev_i32_e32 v33, 31, v32
	s_waitcnt lgkmcnt(0)
	v_readfirstlane_b32 s15, v3
	v_readfirstlane_b32 s14, v2
	v_lshlrev_b64 v[2:3], 2, v[32:33]
	v_lshl_add_u64 v[56:57], s[0:1], 0, v[2:3]
	v_lshl_add_u64 v[6:7], s[14:15], 0, v[2:3]
	v_lshl_add_u64 v[34:35], v[6:7], 0, s[10:11]
	v_add_co_u32_e32 v6, vcc, s3, v34
	s_lshl_b64 s[0:1], s[38:39], 2
	s_nop 0
	v_addc_co_u32_e32 v7, vcc, 0, v35, vcc
	s_waitcnt vmcnt(0)
	flat_load_dwordx2 v[58:59], v[6:7]
	flat_load_dwordx2 v[60:61], v[56:57]
	v_add_co_u32_e32 v6, vcc, s17, v56
	s_add_u32 s46, s46, s0
	s_nop 0
	v_addc_co_u32_e32 v7, vcc, 0, v57, vcc
	flat_load_dwordx2 v[62:63], v[6:7]
	v_add_co_u32_e32 v6, vcc, s5, v56
	s_addc_u32 s47, s35, s1
	s_nop 0
	v_addc_co_u32_e32 v7, vcc, 0, v57, vcc
	flat_load_dwordx2 v[64:65], v[6:7]
	v_add_co_u32_e32 v6, vcc, s87, v56
	v_readfirstlane_b32 s23, v5
	s_nop 0
	v_addc_co_u32_e32 v7, vcc, 0, v57, vcc
	flat_load_dwordx2 v[66:67], v[6:7]
	v_add_co_u32_e32 v6, vcc, s6, v56
	v_readfirstlane_b32 s22, v4
	s_nop 0
	v_addc_co_u32_e32 v7, vcc, 0, v57, vcc
	flat_load_dwordx2 v[68:69], v[6:7]
	v_add_co_u32_e32 v6, vcc, s2, v56
	v_lshl_add_u64 v[4:5], s[46:47], 0, v[2:3]
	s_nop 0
	v_addc_co_u32_e32 v7, vcc, 0, v57, vcc
	flat_load_dwordx2 v[70:71], v[6:7]
	v_add_co_u32_e32 v6, vcc, s7, v56
	s_mov_b32 s49, 0x1a000
	s_nop 0
	v_addc_co_u32_e32 v7, vcc, 0, v57, vcc
	flat_load_dwordx2 v[72:73], v[6:7]
	v_add_co_u32_e32 v6, vcc, s16, v56
	s_mov_b32 s88, 0x1b000
	s_nop 0
	v_addc_co_u32_e32 v7, vcc, 0, v57, vcc
	flat_load_dwordx2 v[74:75], v[6:7]
	v_add_co_u32_e32 v6, vcc, s3, v56
	s_mov_b32 s3, 0x16000
	s_nop 0
	v_addc_co_u32_e32 v7, vcc, 0, v57, vcc
	flat_load_dwordx2 v[76:77], v[6:7]
	flat_load_dwordx2 v[78:79], v[4:5]
	s_nop 0
	flat_load_dwordx2 v[4:5], v[34:35]
	v_add_co_u32_e32 v6, vcc, s17, v34
	s_mov_b32 s50, 0x1c000
	s_nop 0
	v_addc_co_u32_e32 v7, vcc, 0, v35, vcc
	flat_load_dwordx2 v[92:93], v[6:7]
	v_add_co_u32_e32 v6, vcc, s5, v34
	s_mov_b32 s89, 0x1d000
	s_nop 0
	v_addc_co_u32_e32 v7, vcc, 0, v35, vcc
	flat_load_dwordx2 v[90:91], v[6:7]
	v_add_co_u32_e32 v6, vcc, s87, v34
	s_mov_b32 s35, 0x1e000
	s_nop 0
	v_addc_co_u32_e32 v7, vcc, 0, v35, vcc
	flat_load_dwordx2 v[88:89], v[6:7]
	v_add_co_u32_e32 v6, vcc, s6, v34
	s_mov_b32 s47, 0x14000
	s_nop 0
	v_addc_co_u32_e32 v7, vcc, 0, v35, vcc
	flat_load_dwordx2 v[86:87], v[6:7]
	v_add_co_u32_e32 v6, vcc, s2, v34
	s_mov_b32 s2, 0xa000
	s_nop 0
	v_addc_co_u32_e32 v7, vcc, 0, v35, vcc
	flat_load_dwordx2 v[84:85], v[6:7]
	v_add_co_u32_e32 v6, vcc, s7, v34
	s_mov_b32 s58, 0xb000
	s_nop 0
	v_addc_co_u32_e32 v7, vcc, 0, v35, vcc
	flat_load_dwordx2 v[82:83], v[6:7]
	v_add_co_u32_e32 v6, vcc, s16, v34
	s_mov_b32 s8, 0xc000
	s_nop 0
	v_addc_co_u32_e32 v7, vcc, 0, v35, vcc
	flat_load_dwordx2 v[80:81], v[6:7]
	s_mov_b32 s59, 0xd000
	s_mov_b32 s51, 0xe000
	s_mov_b32 s60, 0xf000
	s_mov_b32 s27, 0x10000
	s_mov_b32 s61, 0x11000
	s_mov_b32 s46, 0x12000
	s_mov_b32 s82, 0x13000
	s_add_u32 s14, s76, s10
	s_mov_b32 s53, 0x9000
	s_addc_u32 s15, s77, s11
	v_lshl_add_u64 v[2:3], s[14:15], 0, v[2:3]
	s_mul_i32 s14, s28, 0x7000
	s_mul_hi_i32 s15, s28, 0x7000
	s_add_u32 s14, s92, s14
	s_addc_u32 s15, s93, s15
	v_lshl_add_u64 v[32:33], v[32:33], 1, s[14:15]
	s_mov_b32 s14, 0xe002000
	s_mov_b32 s97, 0x10000
	s_waitcnt vmcnt(0) lgkmcnt(0)
	v_pk_fma_f32 v[4:5], v[60:61], v[4:5], v[78:79]
	s_nop 0
	v_pk_fma_f32 v[4:5], v[62:63], v[92:93], v[4:5]
	v_pk_fma_f32 v[92:93], v[60:61], v[92:93], v[78:79]
	v_pk_fma_f32 v[4:5], v[64:65], v[90:91], v[4:5]
	v_pk_fma_f32 v[92:93], v[62:63], v[90:91], v[92:93]
	v_pk_fma_f32 v[90:91], v[60:61], v[90:91], v[78:79]
	v_pk_fma_f32 v[4:5], v[66:67], v[88:89], v[4:5]
	v_pk_fma_f32 v[92:93], v[64:65], v[88:89], v[92:93]
	v_pk_fma_f32 v[90:91], v[62:63], v[88:89], v[90:91]
	v_pk_fma_f32 v[88:89], v[60:61], v[88:89], v[78:79]
	v_pk_fma_f32 v[4:5], v[68:69], v[86:87], v[4:5]
	v_pk_fma_f32 v[92:93], v[66:67], v[86:87], v[92:93]
	v_pk_fma_f32 v[88:89], v[62:63], v[86:87], v[88:89]
	v_pk_fma_f32 v[90:91], v[64:65], v[86:87], v[90:91]
	v_pk_fma_f32 v[86:87], v[60:61], v[86:87], v[78:79]
	v_pk_fma_f32 v[4:5], v[70:71], v[84:85], v[4:5]
	v_pk_fma_f32 v[92:93], v[68:69], v[84:85], v[92:93]
	v_pk_fma_f32 v[88:89], v[64:65], v[84:85], v[88:89]
	v_pk_fma_f32 v[90:91], v[66:67], v[84:85], v[90:91]
	v_pk_fma_f32 v[86:87], v[62:63], v[84:85], v[86:87]
	v_pk_fma_f32 v[84:85], v[60:61], v[84:85], v[78:79]
	v_pk_fma_f32 v[4:5], v[72:73], v[82:83], v[4:5]
	v_pk_fma_f32 v[92:93], v[70:71], v[82:83], v[92:93]
	v_pk_fma_f32 v[88:89], v[66:67], v[82:83], v[88:89]
	v_pk_fma_f32 v[84:85], v[62:63], v[82:83], v[84:85]
	v_pk_fma_f32 v[90:91], v[68:69], v[82:83], v[90:91]
	v_pk_fma_f32 v[86:87], v[64:65], v[82:83], v[86:87]
	v_pk_fma_f32 v[4:5], v[74:75], v[80:81], v[4:5]
	v_pk_fma_f32 v[92:93], v[72:73], v[80:81], v[92:93]
	v_pk_fma_f32 v[96:97], v[76:77], v[58:59], v[4:5]
	v_add_co_u32_e32 v4, vcc, s83, v56
	v_pk_fma_f32 v[92:93], v[74:75], v[58:59], v[92:93]
	s_nop 0
	v_addc_co_u32_e32 v5, vcc, 0, v57, vcc
	v_add_co_u32_e32 v6, vcc, s3, v56
	flat_load_dwordx2 v[4:5], v[4:5]
	s_nop 0
	v_addc_co_u32_e32 v7, vcc, 0, v57, vcc
	v_add_co_u32_e32 v8, vcc, s90, v56
	flat_load_dwordx2 v[6:7], v[6:7]
	s_nop 0
	v_addc_co_u32_e32 v9, vcc, 0, v57, vcc
	v_add_co_u32_e32 v10, vcc, s48, v56
	flat_load_dwordx2 v[8:9], v[8:9]
	s_nop 0
	v_addc_co_u32_e32 v11, vcc, 0, v57, vcc
	v_add_co_u32_e32 v12, vcc, s52, v56
	flat_load_dwordx2 v[10:11], v[10:11]
	s_nop 0
	v_addc_co_u32_e32 v13, vcc, 0, v57, vcc
	v_add_co_u32_e32 v14, vcc, s49, v56
	flat_load_dwordx2 v[12:13], v[12:13]
	s_nop 0
	v_addc_co_u32_e32 v15, vcc, 0, v57, vcc
	v_add_co_u32_e32 v16, vcc, s88, v56
	flat_load_dwordx2 v[14:15], v[14:15]
	s_nop 0
	v_addc_co_u32_e32 v17, vcc, 0, v57, vcc
	v_add_co_u32_e32 v24, vcc, s50, v56
	flat_load_dwordx2 v[16:17], v[16:17]
	s_nop 0
	v_addc_co_u32_e32 v25, vcc, 0, v57, vcc
	v_add_co_u32_e32 v26, vcc, s89, v56
	flat_load_dwordx2 v[24:25], v[24:25]
	s_nop 0
	v_addc_co_u32_e32 v27, vcc, 0, v57, vcc
	v_add_co_u32_e32 v28, vcc, s35, v56
	s_mov_b32 s35, 0x16261000
	s_nop 0
	v_addc_co_u32_e32 v29, vcc, 0, v57, vcc
	v_add_co_u32_e32 v30, vcc, s47, v56
	flat_load_dwordx2 v[26:27], v[26:27]
	s_nop 0
	v_addc_co_u32_e32 v31, vcc, 0, v57, vcc
	v_add_co_u32_e32 v36, vcc, s2, v56
	flat_load_dwordx2 v[28:29], v[28:29]
	s_nop 0
	v_addc_co_u32_e32 v37, vcc, 0, v57, vcc
	v_add_co_u32_e32 v38, vcc, s58, v56
	flat_load_dwordx2 v[30:31], v[30:31]
	s_nop 0
	v_addc_co_u32_e32 v39, vcc, 0, v57, vcc
	v_add_co_u32_e32 v40, vcc, s8, v56
	flat_load_dwordx2 v[36:37], v[36:37]
	s_nop 0
	v_addc_co_u32_e32 v41, vcc, 0, v57, vcc
	v_add_co_u32_e32 v42, vcc, s59, v56
	flat_load_dwordx2 v[38:39], v[38:39]
	s_nop 0
	v_addc_co_u32_e32 v43, vcc, 0, v57, vcc
	v_add_co_u32_e32 v44, vcc, s51, v56
	flat_load_dwordx2 v[40:41], v[40:41]
	s_nop 0
	v_addc_co_u32_e32 v45, vcc, 0, v57, vcc
	v_add_co_u32_e32 v46, vcc, s60, v56
	flat_load_dwordx2 v[42:43], v[42:43]
	s_nop 0
	v_addc_co_u32_e32 v47, vcc, 0, v57, vcc
	v_add_co_u32_e32 v48, vcc, s27, v56
	flat_load_dwordx2 v[44:45], v[44:45]
	s_nop 0
	v_addc_co_u32_e32 v49, vcc, 0, v57, vcc
	v_add_co_u32_e32 v50, vcc, s61, v56
	flat_load_dwordx2 v[46:47], v[46:47]
	s_nop 0
	v_addc_co_u32_e32 v51, vcc, 0, v57, vcc
	v_add_co_u32_e32 v52, vcc, s46, v56
	flat_load_dwordx2 v[48:49], v[48:49]
	s_nop 0
	v_addc_co_u32_e32 v53, vcc, 0, v57, vcc
	v_add_co_u32_e32 v54, vcc, s82, v56
	flat_load_dwordx2 v[50:51], v[50:51]
	s_nop 0
	v_addc_co_u32_e32 v55, vcc, 0, v57, vcc
	v_add_co_u32_e32 v56, vcc, s53, v56
	flat_load_dwordx2 v[52:53], v[52:53]
	s_nop 0
	v_addc_co_u32_e32 v57, vcc, 0, v57, vcc
	v_add_co_u32_e32 v102, vcc, s35, v2
	flat_load_dwordx2 v[54:55], v[54:55]
	s_nop 0
	v_addc_co_u32_e32 v103, vcc, 0, v3, vcc
	v_add_co_u32_e32 v94, vcc, s53, v34
	flat_load_dwordx2 v[56:57], v[56:57]
	s_nop 0
	v_addc_co_u32_e32 v95, vcc, 0, v35, vcc
	global_store_dwordx2 v[102:103], v[58:59], off offset:-4096
	v_add_co_u32_e32 v204, vcc, 0x9000, v34
	s_nop 1
	v_addc_co_u32_e32 v205, vcc, 0, v35, vcc
	global_load_dwordx2 v[146:147], v[204:205], off
	v_add_co_u32_e32 v204, vcc, 0xa000, v34
	s_nop 1
	v_addc_co_u32_e32 v205, vcc, 0, v35, vcc
	global_load_dwordx2 v[148:149], v[204:205], off
	v_add_co_u32_e32 v204, vcc, 0xb000, v34
	s_nop 1
	v_addc_co_u32_e32 v205, vcc, 0, v35, vcc
	global_load_dwordx2 v[150:151], v[204:205], off
	v_add_co_u32_e32 v204, vcc, 0xc000, v34
	s_nop 1
	v_addc_co_u32_e32 v205, vcc, 0, v35, vcc
	global_load_dwordx2 v[152:153], v[204:205], off
	v_add_co_u32_e32 v204, vcc, 0xd000, v34
	s_nop 1
	v_addc_co_u32_e32 v205, vcc, 0, v35, vcc
	global_load_dwordx2 v[154:155], v[204:205], off
	v_add_co_u32_e32 v204, vcc, 0xe000, v34
	s_nop 1
	v_addc_co_u32_e32 v205, vcc, 0, v35, vcc
	global_load_dwordx2 v[156:157], v[204:205], off
	v_add_co_u32_e32 v204, vcc, 0xf000, v34
	s_nop 1
	v_addc_co_u32_e32 v205, vcc, 0, v35, vcc
	global_load_dwordx2 v[158:159], v[204:205], off
	v_add_co_u32_e32 v204, vcc, 0x10000, v34
	s_nop 1
	v_addc_co_u32_e32 v205, vcc, 0, v35, vcc
	global_load_dwordx2 v[160:161], v[204:205], off
	v_add_co_u32_e32 v204, vcc, 0x11000, v34
	s_nop 1
	v_addc_co_u32_e32 v205, vcc, 0, v35, vcc
	global_load_dwordx2 v[162:163], v[204:205], off
	v_add_co_u32_e32 v204, vcc, 0x12000, v34
	s_nop 1
	v_addc_co_u32_e32 v205, vcc, 0, v35, vcc
	global_load_dwordx2 v[164:165], v[204:205], off
	v_add_co_u32_e32 v204, vcc, 0x13000, v34
	s_nop 1
	v_addc_co_u32_e32 v205, vcc, 0, v35, vcc
	global_load_dwordx2 v[166:167], v[204:205], off
	v_add_co_u32_e32 v204, vcc, 0x14000, v34
	s_nop 1
	v_addc_co_u32_e32 v205, vcc, 0, v35, vcc
	global_load_dwordx2 v[168:169], v[204:205], off
	v_add_co_u32_e32 v204, vcc, 0x15000, v34
	s_nop 1
	v_addc_co_u32_e32 v205, vcc, 0, v35, vcc
	global_load_dwordx2 v[178:179], v[204:205], off
	v_add_co_u32_e32 v204, vcc, 0x16000, v34
	s_nop 1
	v_addc_co_u32_e32 v205, vcc, 0, v35, vcc
	global_load_dwordx2 v[180:181], v[204:205], off
	v_add_co_u32_e32 v204, vcc, 0x17000, v34
	s_nop 1
	v_addc_co_u32_e32 v205, vcc, 0, v35, vcc
	global_load_dwordx2 v[182:183], v[204:205], off
	v_add_co_u32_e32 v204, vcc, 0x18000, v34
	s_nop 1
	v_addc_co_u32_e32 v205, vcc, 0, v35, vcc
	global_load_dwordx2 v[184:185], v[204:205], off
	v_add_co_u32_e32 v204, vcc, 0x19000, v34
	s_nop 1
	v_addc_co_u32_e32 v205, vcc, 0, v35, vcc
	global_load_dwordx2 v[186:187], v[204:205], off
	v_add_co_u32_e32 v204, vcc, 0x1a000, v34
	s_nop 1
	v_addc_co_u32_e32 v205, vcc, 0, v35, vcc
	global_load_dwordx2 v[188:189], v[204:205], off
	v_add_co_u32_e32 v204, vcc, 0x1b000, v34
	s_nop 1
	v_addc_co_u32_e32 v205, vcc, 0, v35, vcc
	global_load_dwordx2 v[190:191], v[204:205], off
	v_add_co_u32_e32 v204, vcc, 0x1c000, v34
	s_nop 1
	v_addc_co_u32_e32 v205, vcc, 0, v35, vcc
	global_load_dwordx2 v[192:193], v[204:205], off
	v_add_co_u32_e32 v204, vcc, 0x1d000, v34
	s_nop 1
	v_addc_co_u32_e32 v205, vcc, 0, v35, vcc
	global_load_dwordx2 v[194:195], v[204:205], off
	s_nop 0
	s_mov_b32 s35, 0x16263000
	v_pk_fma_f32 v[88:89], v[68:69], v[80:81], v[88:89]
	v_pk_fma_f32 v[84:85], v[64:65], v[80:81], v[84:85]
	v_pk_fma_f32 v[88:89], v[70:71], v[58:59], v[88:89]
	v_pk_fma_f32 v[84:85], v[66:67], v[58:59], v[84:85]
	v_pk_fma_f32 v[82:83], v[60:61], v[82:83], v[78:79]
	v_pk_fma_f32 v[90:91], v[70:71], v[80:81], v[90:91]
	v_pk_fma_f32 v[86:87], v[66:67], v[80:81], v[86:87]
	v_pk_fma_f32 v[82:83], v[62:63], v[80:81], v[82:83]
	v_pk_fma_f32 v[60:61], v[60:61], v[80:81], v[78:79]
	v_pk_fma_f32 v[90:91], v[72:73], v[58:59], v[90:91]
	v_pk_fma_f32 v[86:87], v[68:69], v[58:59], v[86:87]
	v_pk_fma_f32 v[82:83], v[64:65], v[58:59], v[82:83]
	v_pk_fma_f32 v[58:59], v[62:63], v[58:59], v[60:61]
	s_waitcnt vmcnt(20) lgkmcnt(0)
	global_store_dwordx2 v[102:103], v[146:147], off
	v_pk_fma_f32 v[102:103], v[76:77], v[146:147], v[92:93]
	v_add_co_u32_e32 v92, vcc, s2, v34
	v_pk_fma_f32 v[88:89], v[72:73], v[146:147], v[88:89]
	s_nop 0
	v_addc_co_u32_e32 v93, vcc, 0, v35, vcc
	s_nop 0
	v_add_co_u32_e32 v92, vcc, s35, v2
	s_mov_b32 s35, 0x16265000
	s_nop 0
	v_addc_co_u32_e32 v93, vcc, 0, v3, vcc
	v_add_co_u32_e32 v104, vcc, s58, v34
	v_pk_fma_f32 v[84:85], v[68:69], v[146:147], v[84:85]
	s_nop 0
	v_addc_co_u32_e32 v105, vcc, 0, v35, vcc
	v_pk_fma_f32 v[96:97], v[56:57], v[146:147], v[96:97]
	v_pk_fma_f32 v[58:59], v[64:65], v[146:147], v[58:59]
	v_pk_fma_f32 v[90:91], v[74:75], v[146:147], v[90:91]
	v_pk_fma_f32 v[86:87], v[70:71], v[146:147], v[86:87]
	v_pk_fma_f32 v[82:83], v[66:67], v[146:147], v[82:83]
	s_mov_b32 s2, 0xc000
	s_waitcnt vmcnt(20) lgkmcnt(0)
	global_store_dwordx2 v[92:93], v[148:149], off offset:-4096
	s_nop 0
	v_pk_fma_f32 v[88:89], v[74:75], v[148:149], v[88:89]
	v_pk_fma_f32 v[84:85], v[70:71], v[148:149], v[84:85]
	v_pk_fma_f32 v[96:97], v[36:37], v[148:149], v[96:97]
	v_pk_fma_f32 v[58:59], v[66:67], v[148:149], v[58:59]
	v_pk_fma_f32 v[82:83], v[68:69], v[148:149], v[82:83]
	v_pk_fma_f32 v[86:87], v[72:73], v[148:149], v[86:87]
	v_pk_fma_f32 v[90:91], v[76:77], v[148:149], v[90:91]
	s_waitcnt vmcnt(20) lgkmcnt(0)
	global_store_dwordx2 v[92:93], v[150:151], off
	v_pk_fma_f32 v[92:93], v[76:77], v[150:151], v[88:89]
	v_add_co_u32_e32 v88, vcc, s8, v34
	v_pk_fma_f32 v[84:85], v[72:73], v[150:151], v[84:85]
	s_nop 0
	v_addc_co_u32_e32 v89, vcc, 0, v35, vcc
	s_nop 0
	v_add_co_u32_e32 v88, vcc, s35, v2
	v_pk_fma_f32 v[96:97], v[38:39], v[150:151], v[96:97]
	s_nop 0
	v_addc_co_u32_e32 v89, vcc, 0, v3, vcc
	v_add_co_u32_e32 v104, vcc, s59, v34
	s_mov_b32 s35, 0x16267000
	s_nop 0
	v_addc_co_u32_e32 v105, vcc, 0, v35, vcc
	v_pk_fma_f32 v[58:59], v[68:69], v[150:151], v[58:59]
	v_pk_fma_f32 v[82:83], v[70:71], v[150:151], v[82:83]
	v_pk_fma_f32 v[86:87], v[74:75], v[150:151], v[86:87]
	s_mov_b32 s8, 0x14000
	s_waitcnt vmcnt(20) lgkmcnt(0)
	global_store_dwordx2 v[88:89], v[152:153], off offset:-4096
	s_nop 0
	v_pk_fma_f32 v[84:85], v[74:75], v[152:153], v[84:85]
	v_pk_fma_f32 v[96:97], v[40:41], v[152:153], v[96:97]
	v_pk_fma_f32 v[58:59], v[70:71], v[152:153], v[58:59]
	v_pk_fma_f32 v[82:83], v[72:73], v[152:153], v[82:83]
	v_pk_fma_f32 v[86:87], v[76:77], v[152:153], v[86:87]
	s_waitcnt vmcnt(20) lgkmcnt(0)
	global_store_dwordx2 v[88:89], v[154:155], off
	v_pk_fma_f32 v[88:89], v[76:77], v[154:155], v[84:85]
	v_add_co_u32_e32 v84, vcc, s51, v34
	v_pk_fma_f32 v[96:97], v[42:43], v[154:155], v[96:97]
	s_nop 0
	v_addc_co_u32_e32 v85, vcc, 0, v35, vcc
	s_nop 0
	v_add_co_u32_e32 v84, vcc, s35, v2
	v_pk_fma_f32 v[58:59], v[72:73], v[154:155], v[58:59]
	s_nop 0
	v_addc_co_u32_e32 v85, vcc, 0, v3, vcc
	s_mov_b32 s35, 0x16269000
	v_pk_fma_f32 v[82:83], v[74:75], v[154:155], v[82:83]
	s_waitcnt vmcnt(20) lgkmcnt(0)
	v_pk_fma_f32 v[110:111], v[44:45], v[156:157], v[96:97]
	v_add_co_u32_e32 v96, vcc, s60, v34
	global_store_dwordx2 v[84:85], v[156:157], off offset:-4096
	s_nop 0
	v_addc_co_u32_e32 v97, vcc, 0, v35, vcc
	s_nop 0
	v_pk_fma_f32 v[58:59], v[74:75], v[156:157], v[58:59]
	v_pk_fma_f32 v[82:83], v[76:77], v[156:157], v[82:83]
	s_waitcnt vmcnt(20) lgkmcnt(0)
	global_store_dwordx2 v[84:85], v[158:159], off
	v_pk_fma_f32 v[84:85], v[76:77], v[158:159], v[58:59]
	v_add_co_u32_e32 v58, vcc, s27, v34
	v_pk_fma_f32 v[110:111], v[46:47], v[158:159], v[110:111]
	s_nop 0
	v_addc_co_u32_e32 v59, vcc, 0, v35, vcc
	s_nop 0
	v_add_co_u32_e32 v58, vcc, s35, v2
	s_mov_b32 s35, 0x1626b000
	s_nop 0
	v_addc_co_u32_e32 v59, vcc, 0, v3, vcc
	v_add_co_u32_e32 v62, vcc, s61, v34
	s_mov_b32 s27, 0x16000
	s_nop 0
	v_addc_co_u32_e32 v63, vcc, 0, v35, vcc
	s_waitcnt vmcnt(20) lgkmcnt(0)
	global_store_dwordx2 v[58:59], v[160:161], off offset:-4096
	v_pk_fma_f32 v[60:61], v[48:49], v[160:161], v[110:111]
	s_nop 0
	s_waitcnt vmcnt(20) lgkmcnt(0)
	global_store_dwordx2 v[58:59], v[162:163], off
	v_pk_fma_f32 v[58:59], v[50:51], v[162:163], v[60:61]
	v_add_co_u32_e32 v60, vcc, s46, v34
	s_nop 1
	v_addc_co_u32_e32 v61, vcc, 0, v35, vcc
	s_nop 0
	v_add_co_u32_e32 v60, vcc, s35, v2
	s_mov_b32 s35, 0x1626d000
	s_nop 0
	v_addc_co_u32_e32 v61, vcc, 0, v3, vcc
	v_add_co_u32_e32 v62, vcc, s82, v34
	s_waitcnt vmcnt(20) lgkmcnt(0)
	global_store_dwordx2 v[60:61], v[164:165], off offset:-4096
	v_addc_co_u32_e32 v63, vcc, 0, v35, vcc
	s_nop 0
	v_pk_fma_f32 v[62:63], v[56:57], v[148:149], v[102:103]
	v_pk_fma_f32 v[58:59], v[52:53], v[164:165], v[58:59]
	v_pk_fma_f32 v[62:63], v[36:37], v[150:151], v[62:63]
	s_waitcnt vmcnt(20) lgkmcnt(0)
	global_store_dwordx2 v[60:61], v[166:167], off
	v_add_co_u32_e32 v60, vcc, s47, v34
	v_pk_fma_f32 v[62:63], v[38:39], v[152:153], v[62:63]
	s_nop 0
	v_addc_co_u32_e32 v61, vcc, 0, v35, vcc
	s_nop 0
	v_pk_fma_f32 v[62:63], v[40:41], v[154:155], v[62:63]
	v_add_co_u32_e32 v60, vcc, s35, v2
	v_pk_fma_f32 v[62:63], v[42:43], v[156:157], v[62:63]
	s_nop 0
	v_addc_co_u32_e32 v61, vcc, 0, v3, vcc
	v_pk_fma_f32 v[62:63], v[44:45], v[158:159], v[62:63]
	s_mov_b32 s35, 0x1626f000
	v_pk_fma_f32 v[62:63], v[46:47], v[160:161], v[62:63]
	v_pk_fma_f32 v[58:59], v[54:55], v[166:167], v[58:59]
	v_pk_fma_f32 v[62:63], v[48:49], v[162:163], v[62:63]
	s_waitcnt vmcnt(20) lgkmcnt(0)
	global_store_dwordx2 v[60:61], v[168:169], off offset:-4096
	v_pk_fma_f32 v[62:63], v[50:51], v[164:165], v[62:63]
	v_pk_fma_f32 v[58:59], v[30:31], v[168:169], v[58:59]
	v_pk_fma_f32 v[62:63], v[52:53], v[166:167], v[62:63]
	s_nop 0
	v_pk_fma_f32 v[76:77], v[54:55], v[168:169], v[62:63]
	v_add_co_u32_e32 v62, vcc, s83, v34
	s_nop 1
	v_addc_co_u32_e32 v63, vcc, 0, v35, vcc
	s_nop 0
	v_pk_fma_f32 v[62:63], v[56:57], v[152:153], v[92:93]
	s_waitcnt vmcnt(20) lgkmcnt(0)
	global_store_dwordx2 v[60:61], v[178:179], off
	v_pk_fma_f32 v[60:61], v[56:57], v[150:151], v[90:91]
	v_pk_fma_f32 v[58:59], v[4:5], v[178:179], v[58:59]
	v_pk_fma_f32 v[60:61], v[36:37], v[152:153], v[60:61]
	v_pk_fma_f32 v[62:63], v[36:37], v[154:155], v[62:63]
	v_pk_fma_f32 v[60:61], v[38:39], v[154:155], v[60:61]
	v_pk_fma_f32 v[62:63], v[38:39], v[156:157], v[62:63]
	v_pk_fma_f32 v[60:61], v[40:41], v[156:157], v[60:61]
	v_pk_fma_f32 v[62:63], v[40:41], v[158:159], v[62:63]
	v_pk_fma_f32 v[60:61], v[42:43], v[158:159], v[60:61]
	v_pk_fma_f32 v[62:63], v[42:43], v[160:161], v[62:63]
	v_pk_fma_f32 v[60:61], v[44:45], v[160:161], v[60:61]
	v_pk_fma_f32 v[62:63], v[44:45], v[162:163], v[62:63]
	v_pk_fma_f32 v[60:61], v[46:47], v[162:163], v[60:61]
	v_pk_fma_f32 v[62:63], v[46:47], v[164:165], v[62:63]
	v_pk_fma_f32 v[60:61], v[48:49], v[164:165], v[60:61]
	v_pk_fma_f32 v[62:63], v[48:49], v[166:167], v[62:63]
	v_pk_fma_f32 v[60:61], v[50:51], v[166:167], v[60:61]
	v_pk_fma_f32 v[62:63], v[50:51], v[168:169], v[62:63]
	v_pk_fma_f32 v[60:61], v[52:53], v[168:169], v[60:61]
	v_pk_fma_f32 v[62:63], v[52:53], v[178:179], v[62:63]
	v_pk_fma_f32 v[68:69], v[54:55], v[178:179], v[60:61]
	v_add_co_u32_e32 v60, vcc, s3, v34
	s_nop 1
	v_addc_co_u32_e32 v61, vcc, 0, v35, vcc
	s_nop 0
	v_add_co_u32_e32 v60, vcc, s35, v2
	s_mov_b32 s35, 0x16271000
	s_nop 0
	v_addc_co_u32_e32 v61, vcc, 0, v3, vcc
	v_add_co_u32_e32 v64, vcc, s90, v34
	s_waitcnt vmcnt(20) lgkmcnt(0)
	global_store_dwordx2 v[60:61], v[180:181], off offset:-4096
	v_addc_co_u32_e32 v65, vcc, 0, v35, vcc
	s_nop 0
	v_add_co_u32_e32 v64, vcc, s48, v34
	v_pk_fma_f32 v[58:59], v[6:7], v[180:181], v[58:59]
	s_nop 0
	v_addc_co_u32_e32 v65, vcc, 0, v35, vcc
	v_add_co_u32_e32 v66, vcc, s35, v2
	s_mov_b32 s35, 0x16273000
	s_nop 0
	v_addc_co_u32_e32 v67, vcc, 0, v3, vcc
	v_add_co_u32_e32 v70, vcc, s52, v34
	v_pk_fma_f32 v[62:63], v[54:55], v[180:181], v[62:63]
	s_nop 0
	v_addc_co_u32_e32 v71, vcc, 0, v35, vcc
	s_waitcnt vmcnt(20) lgkmcnt(0)
	global_store_dwordx2 v[60:61], v[182:183], off
	s_nop 0
	v_pk_fma_f32 v[60:61], v[8:9], v[182:183], v[58:59]
	v_pk_fma_f32 v[58:59], v[56:57], v[154:155], v[86:87]
	s_waitcnt vmcnt(20) lgkmcnt(0)
	global_store_dwordx2 v[66:67], v[184:185], off offset:-4096
	s_nop 0
	v_pk_fma_f32 v[72:73], v[10:11], v[184:185], v[60:61]
	v_pk_fma_f32 v[60:61], v[56:57], v[156:157], v[88:89]
	v_pk_fma_f32 v[58:59], v[36:37], v[156:157], v[58:59]
	v_pk_fma_f32 v[60:61], v[36:37], v[158:159], v[60:61]
	v_pk_fma_f32 v[58:59], v[38:39], v[158:159], v[58:59]
	v_pk_fma_f32 v[60:61], v[38:39], v[160:161], v[60:61]
	v_pk_fma_f32 v[58:59], v[40:41], v[160:161], v[58:59]
	v_pk_fma_f32 v[60:61], v[40:41], v[162:163], v[60:61]
	v_pk_fma_f32 v[58:59], v[42:43], v[162:163], v[58:59]
	v_pk_fma_f32 v[60:61], v[42:43], v[164:165], v[60:61]
	v_pk_fma_f32 v[58:59], v[44:45], v[164:165], v[58:59]
	v_pk_fma_f32 v[60:61], v[44:45], v[166:167], v[60:61]
	v_pk_fma_f32 v[58:59], v[46:47], v[166:167], v[58:59]
	v_pk_fma_f32 v[60:61], v[46:47], v[168:169], v[60:61]
	v_pk_fma_f32 v[58:59], v[48:49], v[168:169], v[58:59]
	v_pk_fma_f32 v[60:61], v[48:49], v[178:179], v[60:61]
	v_pk_fma_f32 v[58:59], v[50:51], v[178:179], v[58:59]
	v_pk_fma_f32 v[60:61], v[50:51], v[180:181], v[60:61]
	v_pk_fma_f32 v[58:59], v[52:53], v[180:181], v[58:59]
	v_pk_fma_f32 v[60:61], v[52:53], v[182:183], v[60:61]
	v_pk_fma_f32 v[58:59], v[54:55], v[182:183], v[58:59]
	v_pk_fma_f32 v[60:61], v[54:55], v[184:185], v[60:61]
	v_pk_fma_f32 v[58:59], v[30:31], v[184:185], v[58:59]
	s_waitcnt vmcnt(20) lgkmcnt(0)
	v_pk_fma_f32 v[86:87], v[12:13], v[186:187], v[72:73]
	v_add_co_u32_e32 v72, vcc, s49, v34
	global_store_dwordx2 v[66:67], v[186:187], off
	s_nop 0
	v_addc_co_u32_e32 v73, vcc, 0, v35, vcc
	s_nop 0
	v_pk_fma_f32 v[66:67], v[56:57], v[158:159], v[82:83]
	v_add_co_u32_e32 v82, vcc, s35, v2
	v_pk_fma_f32 v[56:57], v[56:57], v[160:161], v[84:85]
	v_pk_fma_f32 v[66:67], v[36:37], v[160:161], v[66:67]
	v_addc_co_u32_e32 v83, vcc, 0, v3, vcc
	v_pk_fma_f32 v[36:37], v[36:37], v[162:163], v[56:57]
	v_pk_fma_f32 v[66:67], v[38:39], v[162:163], v[66:67]
	v_pk_fma_f32 v[36:37], v[38:39], v[164:165], v[36:37]
	v_add_co_u32_e32 v38, vcc, s88, v34
	v_pk_fma_f32 v[66:67], v[40:41], v[164:165], v[66:67]
	s_nop 0
	v_addc_co_u32_e32 v39, vcc, 0, v35, vcc
	v_pk_fma_f32 v[36:37], v[40:41], v[166:167], v[36:37]
	v_add_co_u32_e32 v40, vcc, s50, v34
	v_pk_fma_f32 v[66:67], v[42:43], v[166:167], v[66:67]
	s_nop 0
	v_addc_co_u32_e32 v41, vcc, 0, v35, vcc
	v_pk_fma_f32 v[36:37], v[42:43], v[168:169], v[36:37]
	s_mov_b32 s35, 0x16275000
	v_pk_fma_f32 v[66:67], v[44:45], v[168:169], v[66:67]
	v_pk_fma_f32 v[36:37], v[44:45], v[178:179], v[36:37]
	v_add_co_u32_e32 v44, vcc, s35, v2
	v_pk_fma_f32 v[66:67], v[46:47], v[178:179], v[66:67]
	s_nop 0
	v_addc_co_u32_e32 v45, vcc, 0, v3, vcc
	v_add_co_u32_e32 v34, vcc, s89, v34
	v_pk_fma_f32 v[36:37], v[46:47], v[180:181], v[36:37]
	s_nop 0
	v_addc_co_u32_e32 v35, vcc, 0, v35, vcc
	v_pk_fma_f32 v[66:67], v[48:49], v[180:181], v[66:67]
	v_pk_fma_f32 v[36:37], v[48:49], v[182:183], v[36:37]
	v_pk_fma_f32 v[66:67], v[50:51], v[182:183], v[66:67]
	v_pk_fma_f32 v[36:37], v[50:51], v[184:185], v[36:37]
	v_pk_fma_f32 v[66:67], v[52:53], v[184:185], v[66:67]
	v_pk_fma_f32 v[36:37], v[52:53], v[186:187], v[36:37]
	v_pk_fma_f32 v[66:67], v[54:55], v[186:187], v[66:67]
	v_pk_fma_f32 v[58:59], v[4:5], v[186:187], v[58:59]
	v_pk_fma_f32 v[60:61], v[30:31], v[186:187], v[60:61]
	s_waitcnt vmcnt(20) lgkmcnt(0)
	global_store_dwordx2 v[82:83], v[188:189], off offset:-4096
	s_nop 0
	v_pk_fma_f32 v[86:87], v[14:15], v[188:189], v[86:87]
	v_pk_fma_f32 v[36:37], v[54:55], v[188:189], v[36:37]
	v_pk_fma_f32 v[58:59], v[6:7], v[188:189], v[58:59]
	v_pk_fma_f32 v[60:61], v[4:5], v[188:189], v[60:61]
	v_pk_fma_f32 v[66:67], v[30:31], v[188:189], v[66:67]
	s_waitcnt vmcnt(20) lgkmcnt(0)
	global_store_dwordx2 v[82:83], v[190:191], off
	s_nop 0
	v_pk_fma_f32 v[42:43], v[16:17], v[190:191], v[86:87]
	v_pk_fma_f32 v[66:67], v[4:5], v[190:191], v[66:67]
	v_pk_fma_f32 v[60:61], v[6:7], v[190:191], v[60:61]
	v_pk_fma_f32 v[58:59], v[8:9], v[190:191], v[58:59]
	s_waitcnt vmcnt(20) lgkmcnt(0)
	global_store_dwordx2 v[44:45], v[192:193], off offset:-4096
	s_nop 0
	v_pk_fma_f32 v[42:43], v[24:25], v[192:193], v[42:43]
	v_pk_fma_f32 v[66:67], v[6:7], v[192:193], v[66:67]
	v_pk_fma_f32 v[60:61], v[8:9], v[192:193], v[60:61]
	v_pk_fma_f32 v[58:59], v[10:11], v[192:193], v[58:59]
	s_waitcnt vmcnt(20) lgkmcnt(0)
	global_store_dwordx2 v[44:45], v[194:195], off
	v_pk_fma_f32 v[44:45], v[26:27], v[194:195], v[42:43]
	v_add_co_u32_e32 v42, vcc, s14, v32
	s_mov_b32 s14, 0xe003000
	s_nop 0
	v_addc_co_u32_e32 v43, vcc, 0, v33, vcc
	v_add_co_u32_e32 v204, vcc, 0xe002000, v32
	s_nop 1
	v_addc_co_u32_e32 v205, vcc, 0, v33, vcc
	global_load_dword v127, v[204:205], off offset:2048
	v_add_co_u32_e32 v204, vcc, 0xe003000, v32
	s_nop 1
	v_addc_co_u32_e32 v205, vcc, 0, v33, vcc
	global_load_dword v128, v[204:205], off
	v_add_co_u32_e32 v204, vcc, 0xe009000, v32
	s_nop 1
	v_addc_co_u32_e32 v205, vcc, 0, v33, vcc
	global_load_dword v129, v[204:205], off offset:2048
	v_add_co_u32_e32 v204, vcc, 0xe00a000, v32
	s_nop 1
	v_addc_co_u32_e32 v205, vcc, 0, v33, vcc
	global_load_dword v130, v[204:205], off
	v_add_co_u32_e32 v204, vcc, 0xe010000, v32
	s_nop 1
	v_addc_co_u32_e32 v205, vcc, 0, v33, vcc
	global_load_dword v131, v[204:205], off offset:2048
	v_add_co_u32_e32 v204, vcc, 0xe011000, v32
	s_nop 1
	v_addc_co_u32_e32 v205, vcc, 0, v33, vcc
	global_load_dword v132, v[204:205], off
	v_add_co_u32_e32 v204, vcc, 0xe017000, v32
	s_nop 1
	v_addc_co_u32_e32 v205, vcc, 0, v33, vcc
	global_load_dword v133, v[204:205], off offset:2048
	v_add_co_u32_e32 v204, vcc, 0xe018000, v32
	s_nop 1
	v_addc_co_u32_e32 v205, vcc, 0, v33, vcc
	global_load_dword v134, v[204:205], off
	v_add_co_u32_e32 v204, vcc, 0xe01e000, v32
	s_nop 1
	v_addc_co_u32_e32 v205, vcc, 0, v33, vcc
	global_load_dword v135, v[204:205], off offset:2048
	v_add_co_u32_e32 v204, vcc, 0xe01f000, v32
	s_nop 1
	v_addc_co_u32_e32 v205, vcc, 0, v33, vcc
	global_load_dword v136, v[204:205], off
	v_add_co_u32_e32 v204, vcc, 0xe025000, v32
	s_nop 1
	v_addc_co_u32_e32 v205, vcc, 0, v33, vcc
	global_load_dword v196, v[204:205], off offset:2048
	v_add_co_u32_e32 v204, vcc, 0xe026000, v32
	s_nop 1
	v_addc_co_u32_e32 v205, vcc, 0, v33, vcc
	global_load_dword v197, v[204:205], off
	v_add_co_u32_e32 v204, vcc, 0xe02c000, v32
	s_nop 1
	v_addc_co_u32_e32 v205, vcc, 0, v33, vcc
	global_load_dword v198, v[204:205], off offset:2048
	v_add_co_u32_e32 v204, vcc, 0xe02d000, v32
	s_nop 1
	v_addc_co_u32_e32 v205, vcc, 0, v33, vcc
	global_load_dword v199, v[204:205], off
	v_add_co_u32_e32 v204, vcc, 0xe033000, v32
	s_nop 1
	v_addc_co_u32_e32 v205, vcc, 0, v33, vcc
	global_load_dword v206, v[204:205], off offset:2048
	v_add_co_u32_e32 v204, vcc, 0xe034000, v32
	s_nop 1
	v_addc_co_u32_e32 v205, vcc, 0, v33, vcc
	global_load_dword v207, v[204:205], off
	v_add_co_u32_e32 v42, vcc, s14, v32
	s_mov_b32 s14, 0x16277000
	s_nop 0
	v_addc_co_u32_e32 v43, vcc, 0, v33, vcc
	s_nop 0
	v_pk_fma_f32 v[66:67], v[8:9], v[194:195], v[66:67]
	v_pk_fma_f32 v[60:61], v[10:11], v[194:195], v[60:61]
	v_pk_fma_f32 v[58:59], v[12:13], v[194:195], v[58:59]
	s_waitcnt vmcnt(0)
	v_lshlrev_b32_e32 v42, 16, v127
	v_and_b32_e32 v43, 0xffff0000, v127
	s_nop 0
	v_lshlrev_b32_e32 v46, 16, v128
	v_and_b32_e32 v47, 0xffff0000, v128
	v_add_co_u32_e32 v48, vcc, s14, v2
	s_mov_b32 s14, 0xe009000
	s_nop 0
	v_addc_co_u32_e32 v49, vcc, 0, v3, vcc
	v_pk_mul_f32 v[42:43], v[42:43], v[46:47]
	v_add_co_u32_e32 v46, vcc, s14, v32
	global_store_dwordx2 v[48:49], v[42:43], off offset:-4096
	s_nop 0
	v_addc_co_u32_e32 v47, vcc, 0, v33, vcc
	s_mov_b32 s14, 0xe00a000
	s_nop 0
	v_add_co_u32_e32 v46, vcc, s14, v32
	s_mov_b32 s14, 0xe010000
	s_nop 0
	v_addc_co_u32_e32 v47, vcc, 0, v33, vcc
	s_nop 0
	v_pk_fma_f32 v[66:67], v[10:11], v[42:43], v[66:67]
	v_pk_fma_f32 v[60:61], v[12:13], v[42:43], v[60:61]
	v_pk_fma_f32 v[58:59], v[14:15], v[42:43], v[58:59]
	v_pk_fma_f32 v[44:45], v[28:29], v[42:43], v[44:45]
	s_nop 0
	v_lshlrev_b32_e32 v46, 16, v129
	v_and_b32_e32 v47, 0xffff0000, v129
	s_nop 0
	v_lshlrev_b32_e32 v50, 16, v130
	v_and_b32_e32 v51, 0xffff0000, v130
	v_pk_mul_f32 v[46:47], v[46:47], v[50:51]
	v_add_co_u32_e32 v50, vcc, s14, v32
	global_store_dwordx2 v[48:49], v[46:47], off
	s_nop 0
	v_addc_co_u32_e32 v51, vcc, 0, v33, vcc
	s_mov_b32 s14, 0xe011000
	s_nop 0
	v_add_co_u32_e32 v50, vcc, s14, v32
	s_mov_b32 s14, 0x16279000
	s_nop 0
	v_addc_co_u32_e32 v51, vcc, 0, v33, vcc
	s_nop 0
	v_add_co_u32_e32 v56, vcc, s14, v2
	s_mov_b32 s14, 0xe017000
	s_nop 0
	v_addc_co_u32_e32 v57, vcc, 0, v3, vcc
	v_pk_fma_f32 v[48:49], v[30:31], v[178:179], v[76:77]
	v_pk_fma_f32 v[66:67], v[12:13], v[46:47], v[66:67]
	v_pk_fma_f32 v[48:49], v[4:5], v[180:181], v[48:49]
	v_pk_fma_f32 v[60:61], v[14:15], v[46:47], v[60:61]
	v_pk_fma_f32 v[48:49], v[6:7], v[182:183], v[48:49]
	v_pk_fma_f32 v[58:59], v[16:17], v[46:47], v[58:59]
	v_pk_fma_f32 v[48:49], v[8:9], v[184:185], v[48:49]
	s_nop 0
	v_lshlrev_b32_e32 v50, 16, v131
	v_and_b32_e32 v51, 0xffff0000, v131
	v_pk_fma_f32 v[48:49], v[10:11], v[186:187], v[48:49]
	s_nop 0
	v_lshlrev_b32_e32 v52, 16, v132
	v_and_b32_e32 v53, 0xffff0000, v132
	v_pk_mul_f32 v[50:51], v[50:51], v[52:53]
	v_add_co_u32_e32 v54, vcc, s14, v32
	global_store_dwordx2 v[56:57], v[50:51], off offset:-4096
	s_nop 0
	v_addc_co_u32_e32 v55, vcc, 0, v33, vcc
	s_mov_b32 s14, 0xe018000
	v_pk_fma_f32 v[52:53], v[30:31], v[180:181], v[68:69]
	s_nop 0
	v_add_co_u32_e32 v54, vcc, s14, v32
	s_mov_b32 s14, 0xe01e000
	s_nop 0
	v_addc_co_u32_e32 v55, vcc, 0, v33, vcc
	s_nop 0
	v_pk_fma_f32 v[52:53], v[4:5], v[182:183], v[52:53]
	v_pk_fma_f32 v[48:49], v[12:13], v[188:189], v[48:49]
	v_pk_fma_f32 v[52:53], v[6:7], v[184:185], v[52:53]
	v_pk_fma_f32 v[48:49], v[14:15], v[190:191], v[48:49]
	v_pk_fma_f32 v[52:53], v[8:9], v[186:187], v[52:53]
	v_pk_fma_f32 v[48:49], v[16:17], v[192:193], v[48:49]
	v_pk_fma_f32 v[52:53], v[10:11], v[188:189], v[52:53]
	v_pk_fma_f32 v[66:67], v[14:15], v[50:51], v[66:67]
	v_pk_fma_f32 v[52:53], v[12:13], v[190:191], v[52:53]
	v_pk_fma_f32 v[48:49], v[24:25], v[194:195], v[48:49]
	v_pk_fma_f32 v[52:53], v[14:15], v[192:193], v[52:53]
	v_pk_fma_f32 v[60:61], v[16:17], v[50:51], v[60:61]
	v_pk_fma_f32 v[52:53], v[16:17], v[194:195], v[52:53]
	v_pk_fma_f32 v[48:49], v[26:27], v[42:43], v[48:49]
	v_pk_fma_f32 v[52:53], v[24:25], v[42:43], v[52:53]
	v_pk_fma_f32 v[58:59], v[24:25], v[50:51], v[58:59]
	v_pk_fma_f32 v[48:49], v[28:29], v[46:47], v[48:49]
	v_pk_fma_f32 v[52:53], v[26:27], v[46:47], v[52:53]
	s_nop 0
	v_lshlrev_b32_e32 v54, 16, v133
	v_and_b32_e32 v55, 0xffff0000, v133
	v_pk_fma_f32 v[52:53], v[28:29], v[50:51], v[52:53]
	s_nop 0
	v_lshlrev_b32_e32 v68, 16, v134
	v_and_b32_e32 v69, 0xffff0000, v134
	v_pk_mul_f32 v[54:55], v[54:55], v[68:69]
	global_store_dwordx2 v[56:57], v[54:55], off
	v_pk_fma_f32 v[56:57], v[30:31], v[182:183], v[62:63]
	v_add_co_u32_e32 v62, vcc, s14, v32
	s_mov_b32 s14, 0xe01f000
	s_nop 0
	v_addc_co_u32_e32 v63, vcc, 0, v33, vcc
	s_nop 0
	v_add_co_u32_e32 v62, vcc, s14, v32
	s_mov_b32 s14, 0x1627b000
	s_nop 0
	v_addc_co_u32_e32 v63, vcc, 0, v33, vcc
	s_nop 0
	v_pk_fma_f32 v[56:57], v[4:5], v[184:185], v[56:57]
	v_pk_fma_f32 v[66:67], v[16:17], v[54:55], v[66:67]
	v_pk_fma_f32 v[56:57], v[6:7], v[186:187], v[56:57]
	v_pk_fma_f32 v[60:61], v[24:25], v[54:55], v[60:61]
	v_pk_fma_f32 v[56:57], v[8:9], v[188:189], v[56:57]
	v_pk_fma_f32 v[58:59], v[26:27], v[54:55], v[58:59]
	v_pk_fma_f32 v[56:57], v[10:11], v[190:191], v[56:57]
	s_nop 0
	v_lshlrev_b32_e32 v62, 16, v135
	v_and_b32_e32 v63, 0xffff0000, v135
	v_pk_fma_f32 v[56:57], v[12:13], v[192:193], v[56:57]
	s_nop 0
	v_lshlrev_b32_e32 v68, 16, v136
	v_and_b32_e32 v69, 0xffff0000, v136
	v_pk_mul_f32 v[62:63], v[62:63], v[68:69]
	v_add_co_u32_e32 v68, vcc, s14, v2
	s_mov_b32 s14, 0xe025000
	s_nop 0
	v_addc_co_u32_e32 v69, vcc, 0, v3, vcc
	v_add_co_u32_e32 v64, vcc, s14, v32
	global_store_dwordx2 v[68:69], v[62:63], off offset:-4096
	s_nop 0
	v_addc_co_u32_e32 v65, vcc, 0, v33, vcc
	s_mov_b32 s14, 0xe026000
	s_nop 0
	v_add_co_u32_e32 v64, vcc, s14, v32
	s_mov_b32 s14, 0xe02c000
	s_nop 0
	v_addc_co_u32_e32 v65, vcc, 0, v33, vcc
	s_nop 0
	v_pk_fma_f32 v[56:57], v[14:15], v[194:195], v[56:57]
	v_pk_fma_f32 v[66:67], v[24:25], v[62:63], v[66:67]
	v_pk_fma_f32 v[56:57], v[16:17], v[42:43], v[56:57]
	v_pk_fma_f32 v[60:61], v[26:27], v[62:63], v[60:61]
	v_pk_fma_f32 v[56:57], v[24:25], v[46:47], v[56:57]
	v_pk_fma_f32 v[58:59], v[28:29], v[62:63], v[58:59]
	v_pk_fma_f32 v[56:57], v[26:27], v[50:51], v[56:57]
	s_nop 0
	v_lshlrev_b32_e32 v64, 16, v196
	v_and_b32_e32 v65, 0xffff0000, v196
	v_pk_fma_f32 v[56:57], v[28:29], v[54:55], v[56:57]
	s_nop 0
	v_lshlrev_b32_e32 v74, 16, v197
	v_and_b32_e32 v75, 0xffff0000, v197
	v_pk_mul_f32 v[64:65], v[64:65], v[74:75]
	global_store_dwordx2 v[68:69], v[64:65], off
	v_add_co_u32_e32 v68, vcc, s14, v32
	s_mov_b32 s14, 0xe02d000
	s_nop 0
	v_addc_co_u32_e32 v69, vcc, 0, v33, vcc
	s_nop 0
	v_add_co_u32_e32 v68, vcc, s14, v32
	s_mov_b32 s14, 0x1627d000
	s_nop 0
	v_addc_co_u32_e32 v69, vcc, 0, v33, vcc
	s_nop 0
	v_add_co_u32_e32 v2, vcc, s14, v2
	s_mov_b32 s14, 0xe033000
	s_nop 0
	v_addc_co_u32_e32 v3, vcc, 0, v3, vcc
	v_pk_fma_f32 v[66:67], v[26:27], v[64:65], v[66:67]
	v_pk_fma_f32 v[60:61], v[28:29], v[64:65], v[60:61]
	s_nop 0
	v_lshlrev_b32_e32 v68, 16, v198
	v_and_b32_e32 v69, 0xffff0000, v198
	s_nop 0
	v_lshlrev_b32_e32 v70, 16, v199
	v_and_b32_e32 v71, 0xffff0000, v199
	v_pk_mul_f32 v[68:69], v[68:69], v[70:71]
	v_add_co_u32_e32 v70, vcc, s14, v32
	s_mov_b32 s14, 0xe034000
	s_nop 0
	v_addc_co_u32_e32 v71, vcc, 0, v33, vcc
	v_add_co_u32_e32 v32, vcc, s14, v32
	global_store_dwordx2 v[2:3], v[68:69], off offset:-4096
	s_nop 0
	v_addc_co_u32_e32 v33, vcc, 0, v33, vcc
	s_nop 0
	s_andn2_b64 vcc, exec, s[56:57]
	s_nop 0
	v_pk_fma_f32 v[66:67], v[28:29], v[68:69], v[66:67]
	s_nop 0
	v_lshlrev_b32_e32 v32, 16, v206
	v_and_b32_e32 v33, 0xffff0000, v206
	s_nop 0
	v_lshlrev_b32_e32 v70, 16, v207
	v_and_b32_e32 v71, 0xffff0000, v207
	v_pk_mul_f32 v[32:33], v[32:33], v[70:71]
	global_store_dwordx2 v[2:3], v[32:33], off
	v_pk_fma_f32 v[2:3], v[30:31], v[190:191], v[36:37]
	s_nop 0
	v_pk_fma_f32 v[2:3], v[4:5], v[192:193], v[2:3]
	v_lshl_add_u32 v4, v122, 3, 0
	v_pk_fma_f32 v[2:3], v[6:7], v[194:195], v[2:3]
	s_nop 0
	v_pk_fma_f32 v[2:3], v[8:9], v[42:43], v[2:3]
	s_nop 0
	v_pk_fma_f32 v[2:3], v[10:11], v[46:47], v[2:3]
	s_nop 0
	v_pk_fma_f32 v[2:3], v[12:13], v[50:51], v[2:3]
	s_nop 0
	v_pk_fma_f32 v[2:3], v[14:15], v[54:55], v[2:3]
	s_nop 0
	v_pk_fma_f32 v[2:3], v[16:17], v[62:63], v[2:3]
	s_nop 0
	v_pk_fma_f32 v[2:3], v[24:25], v[64:65], v[2:3]
	s_nop 0
	v_pk_fma_f32 v[2:3], v[26:27], v[68:69], v[2:3]
	s_nop 0
	v_pk_fma_f32 v[2:3], v[28:29], v[32:33], v[2:3]
	ds_write2st64_b64 v4, v[44:45], v[48:49] offset1:8
	ds_write2st64_b64 v4, v[52:53], v[56:57] offset0:16 offset1:24
	ds_write2st64_b64 v4, v[58:59], v[60:61] offset0:32 offset1:40
	ds_write2st64_b64 v4, v[66:67], v[2:3] offset0:48 offset1:56
	s_waitcnt lgkmcnt(0)
	s_barrier
	s_cbranch_vccnz .LBB0_638
	v_readlane_b32 s14, v243, 3
	v_and_b32_e32 v2, 64, v203
	v_add_u32_e32 v32, 64, v2
	v_add_u32_e32 v25, s14, v19
	ds_read_b128 v[14:17], v25
	ds_read_b128 v[10:13], v25 offset:16
	v_xor_b32_e32 v2, 1, v203
	v_cmp_lt_i32_e32 vcc, v2, v32
	ds_read_b128 v[6:9], v25 offset:2048
	s_waitcnt lgkmcnt(2)
	v_mov_b32_e32 v3, v16
	v_cndmask_b32_e32 v2, v203, v2, vcc
	v_lshlrev_b32_e32 v33, 2, v2
	v_mov_b32_e32 v2, v15
	v_mov_b32_e32 v4, v14
	v_mov_b32_e32 v5, v17
	v_pk_add_f32 v[2:3], v[2:3], v[4:5]
	s_waitcnt lgkmcnt(1)
	v_mov_b32_e32 v26, v11
	v_add_f32_e32 v2, v2, v3
	v_add_f32_e32 v24, 0, v2
	ds_read_b128 v[2:5], v25 offset:2064
	v_mov_b32_e32 v27, v12
	v_mov_b32_e32 v28, v10
	v_mov_b32_e32 v29, v13
	v_pk_add_f32 v[26:27], v[26:27], v[28:29]
	s_waitcnt lgkmcnt(1)
	v_add_f32_e32 v28, v6, v7
	v_pk_add_f32 v[26:27], v[26:27], v[26:27] op_sel:[0,1] op_sel_hi:[1,0]
	v_add_f32_e32 v30, v8, v9
	s_waitcnt lgkmcnt(0)
	v_mov_b32_e32 v25, v2
	v_mov_b32_e32 v27, v3
	v_mov_b32_e32 v29, v4
	v_mov_b32_e32 v31, v5
	v_pk_add_f32 v[24:25], v[24:25], v[26:27]
	v_pk_add_f32 v[26:27], v[28:29], v[30:31]
	s_add_u32 s22, s22, s0
	v_pk_add_f32 v[24:25], v[24:25], v[26:27]
	v_xor_b32_e32 v26, 2, v203
	v_add_f32_e32 v24, v24, v25
	v_cmp_lt_i32_e32 vcc, v26, v32
	s_addc_u32 s23, s23, s1
	s_add_u32 s0, s34, s0
	v_cndmask_b32_e32 v26, v203, v26, vcc
	v_lshlrev_b32_e32 v36, 2, v26
	v_xor_b32_e32 v26, 4, v203
	v_cmp_lt_i32_e32 vcc, v26, v32
	s_addc_u32 s1, s19, s1
	v_readlane_b32 s14, v244, 27
	v_cndmask_b32_e32 v26, v203, v26, vcc
	v_lshlrev_b32_e32 v37, 2, v26
	v_xor_b32_e32 v26, 8, v203
	v_cmp_lt_i32_e32 vcc, v26, v32
	s_add_u32 s14, s28, s14
	s_addc_u32 s15, s18, 0
	v_cndmask_b32_e32 v26, v203, v26, vcc
	v_lshlrev_b32_e32 v38, 2, v26
	v_xor_b32_e32 v26, 16, v203
	v_cmp_lt_i32_e32 vcc, v26, v32
	s_mul_i32 s18, s15, 0x7000
	s_mul_hi_u32 s19, s14, 0x7000
	v_cndmask_b32_e32 v26, v203, v26, vcc
	v_lshlrev_b32_e32 v39, 2, v26
	v_xor_b32_e32 v26, 32, v203
	v_cmp_lt_i32_e32 vcc, v26, v32
	s_add_i32 s19, s19, s18
	s_mul_i32 s18, s14, 0x7000
	v_cndmask_b32_e32 v26, v203, v26, vcc
	v_lshlrev_b32_e32 v48, 2, v26
	s_add_u32 s18, s92, s18
	s_addc_u32 s19, s93, s19
	v_lshlrev_b32_e32 v172, 2, v125
	s_add_u32 s18, s18, 0x3800
	s_nop 1
	v_add_f32_dpp v24, v24, v24 quad_perm:[1,0,3,2] row_mask:0xf bank_mask:0xf
	s_nop 1
	v_add_f32_dpp v24, v24, v24 quad_perm:[2,3,0,1] row_mask:0xf bank_mask:0xf
	s_nop 1
	v_add_f32_dpp v24, v24, v24 row_half_mirror row_mask:0xf bank_mask:0xf
	s_nop 1
	v_add_f32_dpp v24, v24, v24 row_mirror row_mask:0xf bank_mask:0xf
	s_nop 1
	v_add_f32_dpp v24, v24, v24 row_bcast:15 row_mask:0xa bank_mask:0xf
	s_nop 1
	v_add_f32_dpp v24, v24, v24 row_bcast:31 row_mask:0xc bank_mask:0xf
	s_nop 1
	v_readlane_b32 s100, v24, 63
	v_mov_b32_e32 v32, s100
	v_fmamk_f32 v15, v32, 0xba800000, v15
	v_fmamk_f32 v14, v32, 0xba800000, v14
	v_fmamk_f32 v17, v32, 0xba800000, v17
	v_fmac_f32_e32 v16, 0xba800000, v32
	v_pk_mul_f32 v[24:25], v[16:17], v[16:17]
	v_pk_mul_f32 v[26:27], v[14:15], v[14:15]
	v_fmamk_f32 v11, v32, 0xba800000, v11
	v_pk_mov_b32 v[28:29], v[26:27], v[24:25] op_sel:[1,0]
	v_mov_b32_e32 v27, v25
	v_pk_add_f32 v[24:25], v[28:29], v[26:27]
	v_fmamk_f32 v10, v32, 0xba800000, v10
	v_fmamk_f32 v13, v32, 0xba800000, v13
	v_fmac_f32_e32 v12, 0xba800000, v32
	v_pk_add_f32 v[24:25], v[24:25], v[24:25] op_sel_hi:[0,1]
	v_pk_mul_f32 v[26:27], v[12:13], v[12:13]
	v_pk_mul_f32 v[28:29], v[10:11], v[10:11]
	v_fmamk_f32 v6, v32, 0xba800000, v6
	v_pk_mov_b32 v[30:31], v[28:29], v[26:27] op_sel:[1,0]
	v_mov_b32_e32 v29, v27
	v_fmamk_f32 v7, v32, 0xba800000, v7
	v_fmac_f32_e32 v8, 0xba800000, v32
	v_mul_f32_e32 v24, v6, v6
	v_pk_add_f32 v[26:27], v[30:31], v[28:29]
	v_fmamk_f32 v9, v32, 0xba800000, v9
	v_pk_fma_f32 v[28:29], v[6:7], v[6:7], v[24:25] op_sel_hi:[1,1,0]
	v_mul_f32_e32 v24, v8, v8
	v_pk_add_f32 v[26:27], v[26:27], v[26:27] op_sel_hi:[0,1]
	v_pk_fma_f32 v[30:31], v[8:9], v[8:9], v[24:25] op_sel_hi:[1,1,0]
	v_fmamk_f32 v5, v32, 0xba800000, v5
	v_fmamk_f32 v4, v32, 0xba800000, v4
	v_fmamk_f32 v3, v32, 0xba800000, v3
	v_fmac_f32_e32 v2, 0xba800000, v32
	v_mul_f32_e32 v28, v2, v2
	v_mul_f32_e32 v30, v3, v3
	v_mul_f32_e32 v24, v4, v4
	v_mul_f32_e32 v26, v5, v5
	v_pk_add_f32 v[28:29], v[28:29], v[30:31]
	v_pk_add_f32 v[30:31], v[24:25], v[26:27]
	v_lshl_add_u64 v[44:45], s[0:1], 0, v[172:173]
	v_pk_add_f32 v[28:29], v[28:29], v[30:31]
	v_lshl_add_u64 v[46:47], s[22:23], 0, v[172:173]
	v_add_f32_e32 v40, v28, v29
	s_addc_u32 s19, s19, 0
	flat_load_dwordx4 v[28:31], v[44:45]
	flat_load_dwordx4 v[32:35], v[46:47]
	global_load_dwordx4 v[24:27], v20, s[18:19]
	s_nop 1
	v_add_f32_dpp v40, v40, v40 quad_perm:[1,0,3,2] row_mask:0xf bank_mask:0xf
	s_nop 1
	v_add_f32_dpp v40, v40, v40 quad_perm:[2,3,0,1] row_mask:0xf bank_mask:0xf
	s_nop 1
	v_add_f32_dpp v40, v40, v40 row_half_mirror row_mask:0xf bank_mask:0xf
	s_nop 1
	v_add_f32_dpp v40, v40, v40 row_mirror row_mask:0xf bank_mask:0xf
	s_nop 1
	v_add_f32_dpp v40, v40, v40 row_bcast:15 row_mask:0xa bank_mask:0xf
	s_nop 1
	v_add_f32_dpp v40, v40, v40 row_bcast:31 row_mask:0xc bank_mask:0xf
	s_nop 1
	v_readlane_b32 s100, v40, 63
	flat_load_dwordx4 v[36:39], v[44:45] offset:16
	flat_load_dwordx4 v[40:43], v[46:47] offset:16
	v_mov_b32_e32 v48, s100
	v_fmamk_f32 v48, v48, 0x3a800000, v171
	v_mul_f32_e32 v49, 0x4f800000, v48
	v_cmp_gt_f32_e32 vcc, s9, v48
	s_nop 1
	v_cndmask_b32_e32 v48, v48, v49, vcc
	v_sqrt_f32_e32 v49, v48
	s_nop 0
	v_add_u32_e32 v50, -1, v49
	v_fma_f32 v51, -v50, v49, v48
	v_cmp_ge_f32_e64 s[0:1], 0, v51
	v_add_u32_e32 v51, 1, v49
	s_nop 0
	v_cndmask_b32_e64 v50, v49, v50, s[0:1]
	v_fma_f32 v49, -v51, v49, v48
	v_cmp_lt_f32_e64 s[0:1], 0, v49
	s_nop 1
	v_cndmask_b32_e64 v49, v50, v51, s[0:1]
	v_mul_f32_e32 v50, 0x37800000, v49
	v_cndmask_b32_e32 v49, v49, v50, vcc
	v_cmp_class_f32_e32 vcc, v48, v200
	s_nop 1
	v_cndmask_b32_e32 v48, v49, v48, vcc
	v_div_scale_f32 v49, s[0:1], v48, v48, 1.0
	v_rcp_f32_e32 v50, v49
	s_lshl_b64 s[0:1], s[14:15], 11
	v_fma_f32 v51, -v49, v50, 1.0
	v_fmac_f32_e32 v50, v51, v50
	v_div_scale_f32 v51, vcc, 1.0, v48, 1.0
	v_mul_f32_e32 v52, v51, v50
	v_fma_f32 v53, -v49, v52, v51
	v_fmac_f32_e32 v52, v53, v50
	v_fma_f32 v49, -v49, v52, v51
	v_div_fmas_f32 v49, v49, v50, v52
	v_div_fixup_f32 v48, v49, v48, 1.0
	v_pk_mul_f32 v[14:15], v[14:15], v[48:49] op_sel_hi:[1,0]
	v_pk_mul_f32 v[16:17], v[16:17], v[48:49] op_sel_hi:[1,0]
	v_pk_mul_f32 v[10:11], v[10:11], v[48:49] op_sel_hi:[1,0]
	v_pk_mul_f32 v[12:13], v[12:13], v[48:49] op_sel_hi:[1,0]
	s_waitcnt vmcnt(0) lgkmcnt(0)
	v_pk_fma_f32 v[14:15], v[28:29], v[14:15], v[32:33]
	v_lshlrev_b32_e32 v52, 16, v26
	v_and_b32_e32 v53, 0xffff0000, v26
	v_mul_f32_e32 v26, 0xbfb8aa3b, v14
	v_exp_f32_e32 v26, v26
	v_mul_f32_e32 v28, 0xbfb8aa3b, v15
	v_exp_f32_e32 v29, v28
	v_pk_fma_f32 v[16:17], v[30:31], v[16:17], v[34:35]
	v_add_f32_e32 v26, 1.0, v26
	v_rcp_f32_e32 v28, v26
	v_add_f32_e32 v26, 1.0, v29
	v_mul_f32_e32 v29, 0xbfb8aa3b, v16
	v_exp_f32_e32 v30, v29
	v_mul_f32_e32 v29, 0xbfb8aa3b, v17
	v_exp_f32_e32 v31, v29
	v_rcp_f32_e32 v29, v26
	v_add_f32_e32 v26, 1.0, v30
	v_rcp_f32_e32 v30, v26
	v_add_f32_e32 v26, 1.0, v31
	v_rcp_f32_e32 v31, v26
	v_pk_mul_f32 v[14:15], v[14:15], v[28:29]
	v_lshlrev_b32_e32 v50, 16, v24
	v_pk_fma_f32 v[10:11], v[36:37], v[10:11], v[40:41]
	v_pk_fma_f32 v[12:13], v[38:39], v[12:13], v[42:43]
	v_pk_mul_f32 v[16:17], v[16:17], v[30:31]
	v_mul_f32_e32 v28, 0xbfb8aa3b, v10
	v_mul_f32_e32 v29, 0xbfb8aa3b, v11
	v_mul_f32_e32 v30, 0xbfb8aa3b, v12
	v_mul_f32_e32 v31, 0xbfb8aa3b, v13
	v_exp_f32_e32 v28, v28
	v_exp_f32_e32 v29, v29
	v_exp_f32_e32 v30, v30
	v_exp_f32_e32 v31, v31
	v_add_f32_e32 v28, 1.0, v28
	v_add_f32_e32 v29, 1.0, v29
	v_add_f32_e32 v30, 1.0, v30
	v_add_f32_e32 v31, 1.0, v31
	v_rcp_f32_e32 v28, v28
	v_rcp_f32_e32 v29, v29
	v_rcp_f32_e32 v30, v30
	v_rcp_f32_e32 v31, v31
	v_and_b32_e32 v51, 0xffff0000, v24
	v_lshlrev_b32_e32 v24, 16, v25
	v_and_b32_e32 v25, 0xffff0000, v25
	v_lshlrev_b32_e32 v26, 16, v27
	v_and_b32_e32 v27, 0xffff0000, v27
	v_pk_mul_f32 v[10:11], v[10:11], v[28:29]
	v_pk_mul_f32 v[12:13], v[12:13], v[30:31]
	v_pk_mul_f32 v[16:17], v[16:17], v[24:25]
	v_pk_mul_f32 v[24:25], v[12:13], v[26:27]
	v_pk_mul_f32 v[12:13], v[10:11], v[52:53]
	v_lshl_add_u64 v[36:37], v[22:23], 0, s[0:1]
	v_pk_mul_f32 v[14:15], v[14:15], v[50:51]
	v_pk_mul_f32 v[6:7], v[6:7], v[48:49] op_sel_hi:[1,0]
	v_cvt_pk_bf16_f32 v10, v14, v15
	v_cvt_pk_bf16_f32 v11, v16, v17
	v_cvt_pk_bf16_f32 v12, v12, v13
	v_cvt_pk_bf16_f32 v13, v24, v25
	global_store_dwordx4 v[36:37], v[10:13], off
	global_load_dwordx4 v[14:17], v21, s[18:19]
	s_nop 0
	flat_load_dwordx4 v[10:13], v[46:47] offset:2048
	flat_load_dwordx4 v[24:27], v[44:45] offset:2048
	flat_load_dwordx4 v[28:31], v[44:45] offset:2064
	flat_load_dwordx4 v[32:35], v[46:47] offset:2064
	v_pk_mul_f32 v[8:9], v[8:9], v[48:49] op_sel_hi:[1,0]
	v_pk_mul_f32 v[2:3], v[2:3], v[48:49] op_sel_hi:[1,0]
	v_pk_mul_f32 v[4:5], v[4:5], v[48:49] op_sel_hi:[1,0]
	s_waitcnt vmcnt(0) lgkmcnt(0)
	v_pk_fma_f32 v[6:7], v[24:25], v[6:7], v[10:11]
	v_pk_fma_f32 v[8:9], v[26:27], v[8:9], v[12:13]
	v_mul_f32_e32 v10, 0xbfb8aa3b, v6
	v_mul_f32_e32 v11, 0xbfb8aa3b, v7
	v_mul_f32_e32 v12, 0xbfb8aa3b, v8
	v_mul_f32_e32 v13, 0xbfb8aa3b, v9
	v_exp_f32_e32 v10, v10
	v_exp_f32_e32 v11, v11
	v_exp_f32_e32 v12, v12
	v_exp_f32_e32 v13, v13
	v_add_f32_e32 v10, 1.0, v10
	v_add_f32_e32 v11, 1.0, v11
	v_add_f32_e32 v12, 1.0, v12
	v_add_f32_e32 v13, 1.0, v13
	v_rcp_f32_e32 v10, v10
	v_rcp_f32_e32 v11, v11
	v_rcp_f32_e32 v12, v12
	v_rcp_f32_e32 v13, v13
	v_pk_fma_f32 v[2:3], v[28:29], v[2:3], v[32:33]
	v_pk_fma_f32 v[4:5], v[30:31], v[4:5], v[34:35]
	v_pk_mul_f32 v[6:7], v[6:7], v[10:11]
	v_pk_mul_f32 v[8:9], v[8:9], v[12:13]
	v_mul_f32_e32 v10, 0xbfb8aa3b, v2
	v_mul_f32_e32 v11, 0xbfb8aa3b, v3
	v_mul_f32_e32 v12, 0xbfb8aa3b, v4
	v_mul_f32_e32 v13, 0xbfb8aa3b, v5
	v_exp_f32_e32 v10, v10
	v_exp_f32_e32 v11, v11
	v_exp_f32_e32 v12, v12
	v_exp_f32_e32 v13, v13
	v_add_f32_e32 v10, 1.0, v10
	v_add_f32_e32 v11, 1.0, v11
	v_add_f32_e32 v12, 1.0, v12
	v_add_f32_e32 v13, 1.0, v13
	v_rcp_f32_e32 v10, v10
	v_rcp_f32_e32 v11, v11
	v_rcp_f32_e32 v12, v12
	v_rcp_f32_e32 v13, v13
	v_lshlrev_b32_e32 v40, 16, v16
	v_and_b32_e32 v41, 0xffff0000, v16
	v_lshlrev_b32_e32 v16, 16, v17
	v_and_b32_e32 v17, 0xffff0000, v17
	v_pk_mul_f32 v[2:3], v[2:3], v[10:11]
	v_pk_mul_f32 v[4:5], v[4:5], v[12:13]
	v_lshlrev_b32_e32 v38, 16, v14
	v_and_b32_e32 v39, 0xffff0000, v14
	v_lshlrev_b32_e32 v14, 16, v15
	v_and_b32_e32 v15, 0xffff0000, v15
	v_pk_mul_f32 v[10:11], v[4:5], v[16:17]
	v_pk_mul_f32 v[4:5], v[2:3], v[40:41]
	v_pk_mul_f32 v[8:9], v[8:9], v[14:15]
	v_pk_mul_f32 v[6:7], v[6:7], v[38:39]
	s_nop 0
	v_cvt_pk_bf16_f32 v2, v6, v7
	v_cvt_pk_bf16_f32 v3, v8, v9
	v_cvt_pk_bf16_f32 v4, v4, v5
	v_cvt_pk_bf16_f32 v5, v10, v11
	global_store_dwordx4 v[36:37], v[2:5], off offset:1024
	s_branch .LBB0_638
